# attention epilogue: batched LDS exchange reads, gate loads issued up front, sub-norm weights from LDS, no store-completion waits
# speedup vs baseline: 1.0013x; 1.0013x over previous
.LBB0_301:
	s_cmp_ge_i32 s2, s48
	s_cselect_b64 s[0:1], -1, 0
	s_cmp_lt_i32 s2, s49
	s_cselect_b64 s[2:3], -1, 0
	s_and_b64 s[0:1], s[0:1], s[2:3]
	s_mov_b64 s[52:53], 0
	s_andn2_b64 vcc, exec, s[0:1]
	s_mov_b64 s[16:17], 0
	s_cbranch_vccnz .LBB0_392
	v_writelane_b32 v255, s84, 50
	v_readlane_b32 s4, v252, 25
	v_readlane_b32 s5, v252, 26
	v_writelane_b32 v255, s85, 51
	v_writelane_b32 v255, s72, 52
	s_mov_b32 s85, s37
	s_mov_b32 s84, s37
	v_writelane_b32 v255, s73, 53
	v_writelane_b32 v255, s47, 54
	s_mov_b32 s1, s37
	s_mov_b32 s0, s37
	s_mov_b32 s2, s37
	s_andn2_b64 vcc, exec, s[4:5]
	v_mbcnt_lo_u32_b32 v192, -1, 0
	v_mbcnt_hi_u32_b32 v192, -1, v192
	s_cbranch_vccnz .LBB0_325
	v_readlane_b32 s4, v255, 52
	s_mov_b32 s6, s4
	v_readlane_b32 s5, v255, 53
	v_writelane_b32 v255, s6, 52
	s_mov_b32 s5, s37
	s_lshl_b32 s36, s4, 8
	v_writelane_b32 v255, s7, 53
	s_lshl_b64 s[4:5], s[4:5], 2
	v_readlane_b32 s8, v255, 22
	v_readlane_b32 s9, v255, 23
	s_add_u32 s6, s8, s4
	s_addc_u32 s7, s9, s5
	s_ashr_i32 s67, s85, 31
	v_readlane_b32 s3, v251, 10
	s_add_u32 s52, s3, s85
	v_readlane_b32 s3, v251, 11
	s_addc_u32 s53, s3, s67
	s_ashr_i32 s69, s84, 31
	v_readlane_b32 s3, v254, 12
	s_add_u32 s3, s3, s84
	v_mov_b32_e32 v0, 0x2d604000
	v_writelane_b32 v255, s3, 55
	v_readlane_b32 s3, v254, 13
	s_addc_u32 s3, s3, s69
	s_nop 0
	v_writelane_b32 v255, s3, 56
	s_ashr_i32 s3, s1, 31
	s_add_u32 s1, s30, s1
	s_addc_u32 s3, s31, s3
	s_add_u32 s4, s1, s4
	s_addc_u32 s5, s3, s5
	global_load_dword v193, v0, s[4:5]
	s_ashr_i32 s1, s0, 31
	s_lshl_b64 s[0:1], s[0:1], 3
	s_add_u32 s0, s8, s0
	s_addc_u32 s1, s9, s1
	s_load_dwordx2 s[0:1], s[0:1], 0x90
	s_nop 0
	s_load_dword s3, s[6:7], 0xf0
	s_lshl_b64 s[4:5], s[36:37], 2
	s_waitcnt lgkmcnt(0)
	s_add_u32 s46, s0, s4
	s_addc_u32 s47, s1, s5
	v_lshlrev_b32_e32 v2, 4, v192
	global_load_dwordx4 v[4:7], v2, s[46:47]
	v_add_u32_e32 v2, 0x22800, v2
	s_waitcnt vmcnt(0)
	ds_write_b128 v2, v[4:7]
	s_ashr_i32 s0, s2, 31
	v_readlane_b32 s1, v252, 23
	s_add_u32 s74, s1, s2
	v_readlane_b32 s1, v252, 24
	s_addc_u32 s72, s1, s0
	v_readlane_b32 s0, v255, 11
	s_add_u32 s64, s52, s0
	v_sub_f32_e64 v194, 1.0, s3
	s_addc_u32 s3, s53, 0
	v_readlane_b32 s2, v255, 21
	s_branch .LBB0_305

.LBB0_323:
	s_andn2_b64 vcc, exec, s[42:43]
	s_waitcnt lgkmcnt(0)
	s_barrier
	s_cbranch_vccnz .LBB0_306
	v_div_scale_f32 v3, s[4:5], v0, v0, 1.0
	v_rcp_f32_e32 v4, v3
	s_mov_b64 s[4:5], 0x3000
	v_fma_f32 v5, -v3, v4, 1.0
	v_fmac_f32_e32 v4, v5, v4
	v_div_scale_f32 v5, vcc, 1.0, v0, 1.0
	v_mul_f32_e32 v6, v5, v4
	v_fma_f32 v7, -v3, v6, v5
	v_fmac_f32_e32 v6, v7, v4
	v_fma_f32 v3, -v3, v6, v5
	v_div_fmas_f32 v3, v3, v4, v6
	ds_read2st64_b32 v[232:233], v2 offset0:0 offset1:1
	ds_read2st64_b32 v[234:235], v2 offset0:2 offset1:3
	ds_read2st64_b32 v[236:237], v2 offset0:4 offset1:5
	ds_read2st64_b32 v[238:239], v2 offset0:6 offset1:7
	ds_read2st64_b32 v[240:241], v2 offset0:8 offset1:9
	ds_read2st64_b32 v[242:243], v2 offset0:10 offset1:11
	ds_read2st64_b32 v[244:245], v2 offset0:12 offset1:13
	ds_read2st64_b32 v[246:247], v2 offset0:14 offset1:15
	ds_read2st64_b32 v[208:209], v2 offset0:16 offset1:17
	ds_read2st64_b32 v[210:211], v2 offset0:18 offset1:19
	ds_read2st64_b32 v[212:213], v2 offset0:20 offset1:21
	ds_read2st64_b32 v[214:215], v2 offset0:22 offset1:23
	v_div_fixup_f32 v0, v3, v0, 1.0
	v_add_u32_e32 v10, s35, v205
	v_ashrrev_i32_e32 v11, 31, v10
	v_lshlrev_b64 v[8:9], 14, v[10:11]
	v_lshlrev_b64 v[10:11], 12, v[10:11]
	v_lshl_add_u64 v[8:9], s[52:53], 0, v[8:9]
	v_lshlrev_b32_e32 v6, 3, v195
	v_mov_b32_e32 v7, 0
	v_lshl_add_u64 v[8:9], v[8:9], 0, s[36:37]
	v_lshl_add_u64 v[10:11], s[58:59], 0, v[10:11]
	v_lshl_add_u64 v[8:9], v[8:9], 0, v[6:7]
	v_lshl_add_u64 v[10:11], v[10:11], 0, v[6:7]
	v_lshl_add_u64 v[8:9], v[8:9], 0, s[4:5]
	global_load_dwordx2 v[144:145], v[8:9], off offset:0
	global_load_dwordx2 v[146:147], v[8:9], off offset:16
	global_load_dwordx2 v[148:149], v[8:9], off offset:32
	global_load_dwordx2 v[150:151], v[8:9], off offset:48
	global_load_dwordx2 v[152:153], v[8:9], off offset:64
	global_load_dwordx2 v[154:155], v[8:9], off offset:80
	global_load_dwordx2 v[156:157], v[8:9], off offset:96
	global_load_dwordx2 v[158:159], v[8:9], off offset:112
	global_load_dwordx2 v[160:161], v[8:9], off offset:128
	global_load_dwordx2 v[162:163], v[8:9], off offset:144
	global_load_dwordx2 v[164:165], v[8:9], off offset:160
	global_load_dwordx2 v[166:167], v[8:9], off offset:176
	global_load_dwordx2 v[168:169], v[8:9], off offset:192
	global_load_dwordx2 v[170:171], v[8:9], off offset:208
	global_load_dwordx2 v[172:173], v[8:9], off offset:224
	global_load_dwordx2 v[174:175], v[8:9], off offset:240
	global_load_dwordx2 v[176:177], v[8:9], off offset:256
	global_load_dwordx2 v[178:179], v[8:9], off offset:272
	global_load_dwordx2 v[180:181], v[8:9], off offset:288
	global_load_dwordx2 v[182:183], v[8:9], off offset:304
	global_load_dwordx2 v[184:185], v[8:9], off offset:320
	global_load_dwordx2 v[186:187], v[8:9], off offset:336
	global_load_dwordx2 v[188:189], v[8:9], off offset:352
	global_load_dwordx2 v[190:191], v[8:9], off offset:368
	global_load_dwordx2 v[216:217], v[8:9], off offset:384
	global_load_dwordx2 v[218:219], v[8:9], off offset:400
	global_load_dwordx2 v[220:221], v[8:9], off offset:416
	global_load_dwordx2 v[222:223], v[8:9], off offset:432
	global_load_dwordx2 v[224:225], v[8:9], off offset:448
	global_load_dwordx2 v[226:227], v[8:9], off offset:464
	global_load_dwordx2 v[228:229], v[8:9], off offset:480
	global_load_dwordx2 v[230:231], v[8:9], off offset:496
	v_mov_b32_e32 v12, 0
	v_mov_b32_e32 v13, 0
	v_mov_b32_e32 v14, 0
	v_mov_b32_e32 v15, 0
	s_waitcnt lgkmcnt(8)
	v_fma_f32 v128, v128, v0, -v232
	v_fma_f32 v129, v129, v0, -v233
	v_fma_f32 v130, v130, v0, -v234
	v_fma_f32 v131, v131, v0, -v235
	v_fma_f32 v132, v132, v0, -v236
	v_fma_f32 v133, v133, v0, -v237
	v_fma_f32 v134, v134, v0, -v238
	v_fma_f32 v135, v135, v0, -v239
	v_fmac_f32_e32 v12, v128, v128
	v_fmac_f32_e32 v13, v129, v129
	v_fmac_f32_e32 v14, v130, v130
	v_fmac_f32_e32 v15, v131, v131
	v_fmac_f32_e32 v12, v132, v132
	v_fmac_f32_e32 v13, v133, v133
	v_fmac_f32_e32 v14, v134, v134
	v_fmac_f32_e32 v15, v135, v135
	ds_read2st64_b32 v[232:233], v2 offset0:24 offset1:25
	ds_read2st64_b32 v[234:235], v2 offset0:26 offset1:27
	ds_read2st64_b32 v[236:237], v2 offset0:28 offset1:29
	ds_read2st64_b32 v[238:239], v2 offset0:30 offset1:31
	s_waitcnt lgkmcnt(8)
	v_fma_f32 v136, v136, v0, -v240
	v_fma_f32 v137, v137, v0, -v241
	v_fma_f32 v138, v138, v0, -v242
	v_fma_f32 v139, v139, v0, -v243
	v_fma_f32 v140, v140, v0, -v244
	v_fma_f32 v141, v141, v0, -v245
	v_fma_f32 v142, v142, v0, -v246
	v_fma_f32 v143, v143, v0, -v247
	v_fmac_f32_e32 v12, v136, v136
	v_fmac_f32_e32 v13, v137, v137
	v_fmac_f32_e32 v14, v138, v138
	v_fmac_f32_e32 v15, v139, v139
	v_fmac_f32_e32 v12, v140, v140
	v_fmac_f32_e32 v13, v141, v141
	v_fmac_f32_e32 v14, v142, v142
	v_fmac_f32_e32 v15, v143, v143
	ds_read2st64_b32 v[240:241], v2 offset0:32 offset1:33
	ds_read2st64_b32 v[242:243], v2 offset0:34 offset1:35
	ds_read2st64_b32 v[244:245], v2 offset0:36 offset1:37
	ds_read2st64_b32 v[246:247], v2 offset0:38 offset1:39
	s_waitcnt lgkmcnt(8)
	v_fma_f32 v112, v112, v0, -v208
	v_fma_f32 v113, v113, v0, -v209
	v_fma_f32 v114, v114, v0, -v210
	v_fma_f32 v115, v115, v0, -v211
	v_fma_f32 v116, v116, v0, -v212
	v_fma_f32 v117, v117, v0, -v213
	v_fma_f32 v118, v118, v0, -v214
	v_fma_f32 v119, v119, v0, -v215
	v_fmac_f32_e32 v12, v112, v112
	v_fmac_f32_e32 v13, v113, v113
	v_fmac_f32_e32 v14, v114, v114
	v_fmac_f32_e32 v15, v115, v115
	v_fmac_f32_e32 v12, v116, v116
	v_fmac_f32_e32 v13, v117, v117
	v_fmac_f32_e32 v14, v118, v118
	v_fmac_f32_e32 v15, v119, v119
	ds_read2st64_b32 v[208:209], v2 offset0:40 offset1:41
	ds_read2st64_b32 v[210:211], v2 offset0:42 offset1:43
	ds_read2st64_b32 v[212:213], v2 offset0:44 offset1:45
	ds_read2st64_b32 v[214:215], v2 offset0:46 offset1:47
	s_waitcnt lgkmcnt(8)
	v_fma_f32 v120, v120, v0, -v232
	v_fma_f32 v121, v121, v0, -v233
	v_fma_f32 v122, v122, v0, -v234
	v_fma_f32 v123, v123, v0, -v235
	v_fma_f32 v124, v124, v0, -v236
	v_fma_f32 v125, v125, v0, -v237
	v_fma_f32 v126, v126, v0, -v238
	v_fma_f32 v127, v127, v0, -v239
	v_fmac_f32_e32 v12, v120, v120
	v_fmac_f32_e32 v13, v121, v121
	v_fmac_f32_e32 v14, v122, v122
	v_fmac_f32_e32 v15, v123, v123
	v_fmac_f32_e32 v12, v124, v124
	v_fmac_f32_e32 v13, v125, v125
	v_fmac_f32_e32 v14, v126, v126
	v_fmac_f32_e32 v15, v127, v127
	ds_read2st64_b32 v[232:233], v2 offset0:48 offset1:49
	ds_read2st64_b32 v[234:235], v2 offset0:50 offset1:51
	ds_read2st64_b32 v[236:237], v2 offset0:52 offset1:53
	ds_read2st64_b32 v[238:239], v2 offset0:54 offset1:55
	s_waitcnt lgkmcnt(8)
	v_fma_f32 v96, v96, v0, -v240
	v_fma_f32 v97, v97, v0, -v241
	v_fma_f32 v98, v98, v0, -v242
	v_fma_f32 v99, v99, v0, -v243
	v_fma_f32 v100, v100, v0, -v244
	v_fma_f32 v101, v101, v0, -v245
	v_fma_f32 v102, v102, v0, -v246
	v_fma_f32 v103, v103, v0, -v247
	v_fmac_f32_e32 v12, v96, v96
	v_fmac_f32_e32 v13, v97, v97
	v_fmac_f32_e32 v14, v98, v98
	v_fmac_f32_e32 v15, v99, v99
	v_fmac_f32_e32 v12, v100, v100
	v_fmac_f32_e32 v13, v101, v101
	v_fmac_f32_e32 v14, v102, v102
	v_fmac_f32_e32 v15, v103, v103
	ds_read2st64_b32 v[240:241], v2 offset0:56 offset1:57
	ds_read2st64_b32 v[242:243], v2 offset0:58 offset1:59
	ds_read2st64_b32 v[244:245], v2 offset0:60 offset1:61
	ds_read2st64_b32 v[246:247], v2 offset0:62 offset1:63
	s_waitcnt lgkmcnt(8)
	v_fma_f32 v104, v104, v0, -v208
	v_fma_f32 v105, v105, v0, -v209
	v_fma_f32 v106, v106, v0, -v210
	v_fma_f32 v107, v107, v0, -v211
	v_fma_f32 v108, v108, v0, -v212
	v_fma_f32 v109, v109, v0, -v213
	v_fma_f32 v110, v110, v0, -v214
	v_fma_f32 v111, v111, v0, -v215
	v_fmac_f32_e32 v12, v104, v104
	v_fmac_f32_e32 v13, v105, v105
	v_fmac_f32_e32 v14, v106, v106
	v_fmac_f32_e32 v15, v107, v107
	v_fmac_f32_e32 v12, v108, v108
	v_fmac_f32_e32 v13, v109, v109
	v_fmac_f32_e32 v14, v110, v110
	v_fmac_f32_e32 v15, v111, v111
	ds_read2st64_b32 v[208:209], v2 offset0:64 offset1:65
	ds_read2st64_b32 v[210:211], v2 offset0:66 offset1:67
	ds_read2st64_b32 v[212:213], v2 offset0:68 offset1:69
	ds_read2st64_b32 v[214:215], v2 offset0:70 offset1:71
	s_waitcnt lgkmcnt(8)
	v_fma_f32 v80, v80, v0, -v232
	v_fma_f32 v81, v81, v0, -v233
	v_fma_f32 v82, v82, v0, -v234
	v_fma_f32 v83, v83, v0, -v235
	v_fma_f32 v84, v84, v0, -v236
	v_fma_f32 v85, v85, v0, -v237
	v_fma_f32 v86, v86, v0, -v238
	v_fma_f32 v87, v87, v0, -v239
	v_fmac_f32_e32 v12, v80, v80
	v_fmac_f32_e32 v13, v81, v81
	v_fmac_f32_e32 v14, v82, v82
	v_fmac_f32_e32 v15, v83, v83
	v_fmac_f32_e32 v12, v84, v84
	v_fmac_f32_e32 v13, v85, v85
	v_fmac_f32_e32 v14, v86, v86
	v_fmac_f32_e32 v15, v87, v87
	ds_read2st64_b32 v[232:233], v2 offset0:72 offset1:73
	ds_read2st64_b32 v[234:235], v2 offset0:74 offset1:75
	ds_read2st64_b32 v[236:237], v2 offset0:76 offset1:77
	ds_read2st64_b32 v[238:239], v2 offset0:78 offset1:79
	s_waitcnt lgkmcnt(8)
	v_fma_f32 v88, v88, v0, -v240
	v_fma_f32 v89, v89, v0, -v241
	v_fma_f32 v90, v90, v0, -v242
	v_fma_f32 v91, v91, v0, -v243
	v_fma_f32 v92, v92, v0, -v244
	v_fma_f32 v93, v93, v0, -v245
	v_fma_f32 v94, v94, v0, -v246
	v_fma_f32 v95, v95, v0, -v247
	v_fmac_f32_e32 v12, v88, v88
	v_fmac_f32_e32 v13, v89, v89
	v_fmac_f32_e32 v14, v90, v90
	v_fmac_f32_e32 v15, v91, v91
	v_fmac_f32_e32 v12, v92, v92
	v_fmac_f32_e32 v13, v93, v93
	v_fmac_f32_e32 v14, v94, v94
	v_fmac_f32_e32 v15, v95, v95
	ds_read2st64_b32 v[240:241], v2 offset0:80 offset1:81
	ds_read2st64_b32 v[242:243], v2 offset0:82 offset1:83
	ds_read2st64_b32 v[244:245], v2 offset0:84 offset1:85
	ds_read2st64_b32 v[246:247], v2 offset0:86 offset1:87
	s_waitcnt lgkmcnt(8)
	v_fma_f32 v64, v64, v0, -v208
	v_fma_f32 v65, v65, v0, -v209
	v_fma_f32 v66, v66, v0, -v210
	v_fma_f32 v67, v67, v0, -v211
	v_fma_f32 v68, v68, v0, -v212
	v_fma_f32 v69, v69, v0, -v213
	v_fma_f32 v70, v70, v0, -v214
	v_fma_f32 v71, v71, v0, -v215
	v_fmac_f32_e32 v12, v64, v64
	v_fmac_f32_e32 v13, v65, v65
	v_fmac_f32_e32 v14, v66, v66
	v_fmac_f32_e32 v15, v67, v67
	v_fmac_f32_e32 v12, v68, v68
	v_fmac_f32_e32 v13, v69, v69
	v_fmac_f32_e32 v14, v70, v70
	v_fmac_f32_e32 v15, v71, v71
	ds_read2st64_b32 v[208:209], v2 offset0:88 offset1:89
	ds_read2st64_b32 v[210:211], v2 offset0:90 offset1:91
	ds_read2st64_b32 v[212:213], v2 offset0:92 offset1:93
	ds_read2st64_b32 v[214:215], v2 offset0:94 offset1:95
	s_waitcnt lgkmcnt(8)
	v_fma_f32 v72, v72, v0, -v232
	v_fma_f32 v73, v73, v0, -v233
	v_fma_f32 v74, v74, v0, -v234
	v_fma_f32 v75, v75, v0, -v235
	v_fma_f32 v76, v76, v0, -v236
	v_fma_f32 v77, v77, v0, -v237
	v_fma_f32 v78, v78, v0, -v238
	v_fma_f32 v79, v79, v0, -v239
	v_fmac_f32_e32 v12, v72, v72
	v_fmac_f32_e32 v13, v73, v73
	v_fmac_f32_e32 v14, v74, v74
	v_fmac_f32_e32 v15, v75, v75
	v_fmac_f32_e32 v12, v76, v76
	v_fmac_f32_e32 v13, v77, v77
	v_fmac_f32_e32 v14, v78, v78
	v_fmac_f32_e32 v15, v79, v79
	ds_read2st64_b32 v[232:233], v2 offset0:96 offset1:97
	ds_read2st64_b32 v[234:235], v2 offset0:98 offset1:99
	ds_read2st64_b32 v[236:237], v2 offset0:100 offset1:101
	ds_read2st64_b32 v[238:239], v2 offset0:102 offset1:103
	s_waitcnt lgkmcnt(8)
	v_fma_f32 v48, v48, v0, -v240
	v_fma_f32 v49, v49, v0, -v241
	v_fma_f32 v50, v50, v0, -v242
	v_fma_f32 v51, v51, v0, -v243
	v_fma_f32 v52, v52, v0, -v244
	v_fma_f32 v53, v53, v0, -v245
	v_fma_f32 v54, v54, v0, -v246
	v_fma_f32 v55, v55, v0, -v247
	v_fmac_f32_e32 v12, v48, v48
	v_fmac_f32_e32 v13, v49, v49
	v_fmac_f32_e32 v14, v50, v50
	v_fmac_f32_e32 v15, v51, v51
	v_fmac_f32_e32 v12, v52, v52
	v_fmac_f32_e32 v13, v53, v53
	v_fmac_f32_e32 v14, v54, v54
	v_fmac_f32_e32 v15, v55, v55
	ds_read2st64_b32 v[240:241], v2 offset0:104 offset1:105
	ds_read2st64_b32 v[242:243], v2 offset0:106 offset1:107
	ds_read2st64_b32 v[244:245], v2 offset0:108 offset1:109
	ds_read2st64_b32 v[246:247], v2 offset0:110 offset1:111
	s_waitcnt lgkmcnt(8)
	v_fma_f32 v56, v56, v0, -v208
	v_fma_f32 v57, v57, v0, -v209
	v_fma_f32 v58, v58, v0, -v210
	v_fma_f32 v59, v59, v0, -v211
	v_fma_f32 v60, v60, v0, -v212
	v_fma_f32 v61, v61, v0, -v213
	v_fma_f32 v62, v62, v0, -v214
	v_fma_f32 v63, v63, v0, -v215
	v_fmac_f32_e32 v12, v56, v56
	v_fmac_f32_e32 v13, v57, v57
	v_fmac_f32_e32 v14, v58, v58
	v_fmac_f32_e32 v15, v59, v59
	v_fmac_f32_e32 v12, v60, v60
	v_fmac_f32_e32 v13, v61, v61
	v_fmac_f32_e32 v14, v62, v62
	v_fmac_f32_e32 v15, v63, v63
	ds_read2st64_b32 v[208:209], v2 offset0:112 offset1:113
	ds_read2st64_b32 v[210:211], v2 offset0:114 offset1:115
	ds_read2st64_b32 v[212:213], v2 offset0:116 offset1:117
	ds_read2st64_b32 v[214:215], v2 offset0:118 offset1:119
	s_waitcnt lgkmcnt(8)
	v_fma_f32 v32, v32, v0, -v232
	v_fma_f32 v33, v33, v0, -v233
	v_fma_f32 v34, v34, v0, -v234
	v_fma_f32 v35, v35, v0, -v235
	v_fma_f32 v36, v36, v0, -v236
	v_fma_f32 v37, v37, v0, -v237
	v_fma_f32 v38, v38, v0, -v238
	v_fma_f32 v39, v39, v0, -v239
	v_fmac_f32_e32 v12, v32, v32
	v_fmac_f32_e32 v13, v33, v33
	v_fmac_f32_e32 v14, v34, v34
	v_fmac_f32_e32 v15, v35, v35
	v_fmac_f32_e32 v12, v36, v36
	v_fmac_f32_e32 v13, v37, v37
	v_fmac_f32_e32 v14, v38, v38
	v_fmac_f32_e32 v15, v39, v39
	ds_read2st64_b32 v[232:233], v2 offset0:120 offset1:121
	ds_read2st64_b32 v[234:235], v2 offset0:122 offset1:123
	ds_read2st64_b32 v[236:237], v2 offset0:124 offset1:125
	ds_read2st64_b32 v[238:239], v2 offset0:126 offset1:127
	s_waitcnt lgkmcnt(8)
	v_fma_f32 v40, v40, v0, -v240
	v_fma_f32 v41, v41, v0, -v241
	v_fma_f32 v42, v42, v0, -v242
	v_fma_f32 v43, v43, v0, -v243
	v_fma_f32 v44, v44, v0, -v244
	v_fma_f32 v45, v45, v0, -v245
	v_fma_f32 v46, v46, v0, -v246
	v_fma_f32 v47, v47, v0, -v247
	v_fmac_f32_e32 v12, v40, v40
	v_fmac_f32_e32 v13, v41, v41
	v_fmac_f32_e32 v14, v42, v42
	v_fmac_f32_e32 v15, v43, v43
	v_fmac_f32_e32 v12, v44, v44
	v_fmac_f32_e32 v13, v45, v45
	v_fmac_f32_e32 v14, v46, v46
	v_fmac_f32_e32 v15, v47, v47
	s_waitcnt lgkmcnt(4)
	v_fma_f32 v16, v16, v0, -v208
	v_fma_f32 v17, v17, v0, -v209
	v_fma_f32 v18, v18, v0, -v210
	v_fma_f32 v19, v19, v0, -v211
	v_fma_f32 v20, v20, v0, -v212
	v_fma_f32 v21, v21, v0, -v213
	v_fma_f32 v22, v22, v0, -v214
	v_fma_f32 v23, v23, v0, -v215
	v_fmac_f32_e32 v12, v16, v16
	v_fmac_f32_e32 v13, v17, v17
	v_fmac_f32_e32 v14, v18, v18
	v_fmac_f32_e32 v15, v19, v19
	v_fmac_f32_e32 v12, v20, v20
	v_fmac_f32_e32 v13, v21, v21
	v_fmac_f32_e32 v14, v22, v22
	v_fmac_f32_e32 v15, v23, v23
	s_waitcnt lgkmcnt(0)
	v_fma_f32 v24, v24, v0, -v232
	v_fma_f32 v25, v25, v0, -v233
	v_fma_f32 v26, v26, v0, -v234
	v_fma_f32 v27, v27, v0, -v235
	v_fma_f32 v28, v28, v0, -v236
	v_fma_f32 v29, v29, v0, -v237
	v_fma_f32 v30, v30, v0, -v238
	v_fma_f32 v31, v31, v0, -v239
	v_fmac_f32_e32 v12, v24, v24
	v_fmac_f32_e32 v13, v25, v25
	v_fmac_f32_e32 v14, v26, v26
	v_fmac_f32_e32 v15, v27, v27
	v_fmac_f32_e32 v12, v28, v28
	v_fmac_f32_e32 v13, v29, v29
	v_fmac_f32_e32 v14, v30, v30
	v_fmac_f32_e32 v15, v31, v31
	v_lshlrev_b32_e32 v2, 4, v195
	v_add_u32_e32 v2, 0x22800, v2
	ds_read_b128 v[232:235], v2 offset:0
	ds_read_b128 v[236:239], v2 offset:32
	ds_read_b128 v[240:243], v2 offset:64
	ds_read_b128 v[244:247], v2 offset:96
	ds_read_b128 v[208:211], v2 offset:128
	ds_read_b128 v[212:215], v2 offset:160
	v_add_f32_e32 v12, v12, v13
	v_add_f32_e32 v14, v14, v15
	v_add_f32_e32 v12, v12, v14
	v_mov_b32_e32 v13, v12
	s_nop 1
	v_permlane32_swap_b32_e32 v12, v13
	v_add_f32_e32 v12, v12, v13
	v_mov_b32_e32 v13, 0x3727c5ac
	v_fmamk_f32 v12, v12, 0x3b800000, v13
	v_cmp_gt_f32_e32 vcc, s81, v12
	v_mul_f32_e32 v13, 0x4b800000, v12
	s_nop 0
	v_cndmask_b32_e32 v12, v12, v13, vcc
	v_rsq_f32_e32 v12, v12
	s_nop 0
	v_mul_f32_e32 v13, 0x45800000, v12
	v_cndmask_b32_e32 v12, v12, v13, vcc
	v_mul_f32_e32 v0, v194, v12
	s_waitcnt lgkmcnt(4)
	s_waitcnt vmcnt(31)
	v_mul_f32_e32 v4, v128, v0
	v_mul_f32_e32 v3, v129, v0
	v_mul_f32_e32 v4, v232, v4
	v_mul_f32_e32 v3, v233, v3
	v_lshlrev_b32_e32 v14, 16, v144
	v_and_b32_e32 v144, 0xffff0000, v144
	v_mul_f32_e32 v4, v4, v14
	v_mul_f32_e32 v3, v3, v144
	v_cvt_pk_bf16_f32 v4, v4, v3
	v_mul_f32_e32 v5, v130, v0
	v_mul_f32_e32 v3, v131, v0
	v_mul_f32_e32 v5, v234, v5
	v_mul_f32_e32 v3, v235, v3
	v_lshlrev_b32_e32 v14, 16, v145
	v_and_b32_e32 v145, 0xffff0000, v145
	v_mul_f32_e32 v5, v5, v14
	v_mul_f32_e32 v3, v3, v145
	v_cvt_pk_bf16_f32 v5, v5, v3
	global_store_dwordx2 v[10:11], v[4:5], off offset:0
	s_waitcnt vmcnt(31)
	v_mul_f32_e32 v6, v132, v0
	v_mul_f32_e32 v9, v133, v0
	v_mul_f32_e32 v6, v236, v6
	v_mul_f32_e32 v9, v237, v9
	v_lshlrev_b32_e32 v15, 16, v146
	v_and_b32_e32 v146, 0xffff0000, v146
	v_mul_f32_e32 v6, v6, v15
	v_mul_f32_e32 v9, v9, v146
	v_cvt_pk_bf16_f32 v6, v6, v9
	v_mul_f32_e32 v7, v134, v0
	v_mul_f32_e32 v9, v135, v0
	v_mul_f32_e32 v7, v238, v7
	v_mul_f32_e32 v9, v239, v9
	v_lshlrev_b32_e32 v15, 16, v147
	v_and_b32_e32 v147, 0xffff0000, v147
	v_mul_f32_e32 v7, v7, v15
	v_mul_f32_e32 v9, v9, v147
	v_cvt_pk_bf16_f32 v7, v7, v9
	global_store_dwordx2 v[10:11], v[6:7], off offset:16
	ds_read_b128 v[232:235], v2 offset:192
	ds_read_b128 v[236:239], v2 offset:224
	s_waitcnt lgkmcnt(4)
	s_waitcnt vmcnt(31)
	v_mul_f32_e32 v4, v136, v0
	v_mul_f32_e32 v3, v137, v0
	v_mul_f32_e32 v4, v240, v4
	v_mul_f32_e32 v3, v241, v3
	v_lshlrev_b32_e32 v14, 16, v148
	v_and_b32_e32 v148, 0xffff0000, v148
	v_mul_f32_e32 v4, v4, v14
	v_mul_f32_e32 v3, v3, v148
	v_cvt_pk_bf16_f32 v4, v4, v3
	v_mul_f32_e32 v5, v138, v0
	v_mul_f32_e32 v3, v139, v0
	v_mul_f32_e32 v5, v242, v5
	v_mul_f32_e32 v3, v243, v3
	v_lshlrev_b32_e32 v14, 16, v149
	v_and_b32_e32 v149, 0xffff0000, v149
	v_mul_f32_e32 v5, v5, v14
	v_mul_f32_e32 v3, v3, v149
	v_cvt_pk_bf16_f32 v5, v5, v3
	global_store_dwordx2 v[10:11], v[4:5], off offset:32
	s_waitcnt vmcnt(31)
	v_mul_f32_e32 v6, v140, v0
	v_mul_f32_e32 v9, v141, v0
	v_mul_f32_e32 v6, v244, v6
	v_mul_f32_e32 v9, v245, v9
	v_lshlrev_b32_e32 v15, 16, v150
	v_and_b32_e32 v150, 0xffff0000, v150
	v_mul_f32_e32 v6, v6, v15
	v_mul_f32_e32 v9, v9, v150
	v_cvt_pk_bf16_f32 v6, v6, v9
	v_mul_f32_e32 v7, v142, v0
	v_mul_f32_e32 v9, v143, v0
	v_mul_f32_e32 v7, v246, v7
	v_mul_f32_e32 v9, v247, v9
	v_lshlrev_b32_e32 v15, 16, v151
	v_and_b32_e32 v151, 0xffff0000, v151
	v_mul_f32_e32 v7, v7, v15
	v_mul_f32_e32 v9, v9, v151
	v_cvt_pk_bf16_f32 v7, v7, v9
	global_store_dwordx2 v[10:11], v[6:7], off offset:48
	ds_read_b128 v[240:243], v2 offset:256
	ds_read_b128 v[244:247], v2 offset:288
	s_waitcnt lgkmcnt(4)
	s_waitcnt vmcnt(31)
	v_mul_f32_e32 v4, v112, v0
	v_mul_f32_e32 v3, v113, v0
	v_mul_f32_e32 v4, v208, v4
	v_mul_f32_e32 v3, v209, v3
	v_lshlrev_b32_e32 v14, 16, v152
	v_and_b32_e32 v152, 0xffff0000, v152
	v_mul_f32_e32 v4, v4, v14
	v_mul_f32_e32 v3, v3, v152
	v_cvt_pk_bf16_f32 v4, v4, v3
	v_mul_f32_e32 v5, v114, v0
	v_mul_f32_e32 v3, v115, v0
	v_mul_f32_e32 v5, v210, v5
	v_mul_f32_e32 v3, v211, v3
	v_lshlrev_b32_e32 v14, 16, v153
	v_and_b32_e32 v153, 0xffff0000, v153
	v_mul_f32_e32 v5, v5, v14
	v_mul_f32_e32 v3, v3, v153
	v_cvt_pk_bf16_f32 v5, v5, v3
	global_store_dwordx2 v[10:11], v[4:5], off offset:64
	s_waitcnt vmcnt(31)
	v_mul_f32_e32 v6, v116, v0
	v_mul_f32_e32 v9, v117, v0
	v_mul_f32_e32 v6, v212, v6
	v_mul_f32_e32 v9, v213, v9
	v_lshlrev_b32_e32 v15, 16, v154
	v_and_b32_e32 v154, 0xffff0000, v154
	v_mul_f32_e32 v6, v6, v15
	v_mul_f32_e32 v9, v9, v154
	v_cvt_pk_bf16_f32 v6, v6, v9
	v_mul_f32_e32 v7, v118, v0
	v_mul_f32_e32 v9, v119, v0
	v_mul_f32_e32 v7, v214, v7
	v_mul_f32_e32 v9, v215, v9
	v_lshlrev_b32_e32 v15, 16, v155
	v_and_b32_e32 v155, 0xffff0000, v155
	v_mul_f32_e32 v7, v7, v15
	v_mul_f32_e32 v9, v9, v155
	v_cvt_pk_bf16_f32 v7, v7, v9
	global_store_dwordx2 v[10:11], v[6:7], off offset:80
	ds_read_b128 v[208:211], v2 offset:320
	ds_read_b128 v[212:215], v2 offset:352
	s_waitcnt lgkmcnt(4)
	s_waitcnt vmcnt(31)
	v_mul_f32_e32 v4, v120, v0
	v_mul_f32_e32 v3, v121, v0
	v_mul_f32_e32 v4, v232, v4
	v_mul_f32_e32 v3, v233, v3
	v_lshlrev_b32_e32 v14, 16, v156
	v_and_b32_e32 v156, 0xffff0000, v156
	v_mul_f32_e32 v4, v4, v14
	v_mul_f32_e32 v3, v3, v156
	v_cvt_pk_bf16_f32 v4, v4, v3
	v_mul_f32_e32 v5, v122, v0
	v_mul_f32_e32 v3, v123, v0
	v_mul_f32_e32 v5, v234, v5
	v_mul_f32_e32 v3, v235, v3
	v_lshlrev_b32_e32 v14, 16, v157
	v_and_b32_e32 v157, 0xffff0000, v157
	v_mul_f32_e32 v5, v5, v14
	v_mul_f32_e32 v3, v3, v157
	v_cvt_pk_bf16_f32 v5, v5, v3
	global_store_dwordx2 v[10:11], v[4:5], off offset:96
	s_waitcnt vmcnt(31)
	v_mul_f32_e32 v6, v124, v0
	v_mul_f32_e32 v9, v125, v0
	v_mul_f32_e32 v6, v236, v6
	v_mul_f32_e32 v9, v237, v9
	v_lshlrev_b32_e32 v15, 16, v158
	v_and_b32_e32 v158, 0xffff0000, v158
	v_mul_f32_e32 v6, v6, v15
	v_mul_f32_e32 v9, v9, v158
	v_cvt_pk_bf16_f32 v6, v6, v9
	v_mul_f32_e32 v7, v126, v0
	v_mul_f32_e32 v9, v127, v0
	v_mul_f32_e32 v7, v238, v7
	v_mul_f32_e32 v9, v239, v9
	v_lshlrev_b32_e32 v15, 16, v159
	v_and_b32_e32 v159, 0xffff0000, v159
	v_mul_f32_e32 v7, v7, v15
	v_mul_f32_e32 v9, v9, v159
	v_cvt_pk_bf16_f32 v7, v7, v9
	global_store_dwordx2 v[10:11], v[6:7], off offset:112
	ds_read_b128 v[232:235], v2 offset:384
	ds_read_b128 v[236:239], v2 offset:416
	s_waitcnt lgkmcnt(4)
	s_waitcnt vmcnt(31)
	v_mul_f32_e32 v4, v96, v0
	v_mul_f32_e32 v3, v97, v0
	v_mul_f32_e32 v4, v240, v4
	v_mul_f32_e32 v3, v241, v3
	v_lshlrev_b32_e32 v14, 16, v160
	v_and_b32_e32 v160, 0xffff0000, v160
	v_mul_f32_e32 v4, v4, v14
	v_mul_f32_e32 v3, v3, v160
	v_cvt_pk_bf16_f32 v4, v4, v3
	v_mul_f32_e32 v5, v98, v0
	v_mul_f32_e32 v3, v99, v0
	v_mul_f32_e32 v5, v242, v5
	v_mul_f32_e32 v3, v243, v3
	v_lshlrev_b32_e32 v14, 16, v161
	v_and_b32_e32 v161, 0xffff0000, v161
	v_mul_f32_e32 v5, v5, v14
	v_mul_f32_e32 v3, v3, v161
	v_cvt_pk_bf16_f32 v5, v5, v3
	global_store_dwordx2 v[10:11], v[4:5], off offset:128
	s_waitcnt vmcnt(31)
	v_mul_f32_e32 v6, v100, v0
	v_mul_f32_e32 v9, v101, v0
	v_mul_f32_e32 v6, v244, v6
	v_mul_f32_e32 v9, v245, v9
	v_lshlrev_b32_e32 v15, 16, v162
	v_and_b32_e32 v162, 0xffff0000, v162
	v_mul_f32_e32 v6, v6, v15
	v_mul_f32_e32 v9, v9, v162
	v_cvt_pk_bf16_f32 v6, v6, v9
	v_mul_f32_e32 v7, v102, v0
	v_mul_f32_e32 v9, v103, v0
	v_mul_f32_e32 v7, v246, v7
	v_mul_f32_e32 v9, v247, v9
	v_lshlrev_b32_e32 v15, 16, v163
	v_and_b32_e32 v163, 0xffff0000, v163
	v_mul_f32_e32 v7, v7, v15
	v_mul_f32_e32 v9, v9, v163
	v_cvt_pk_bf16_f32 v7, v7, v9
	global_store_dwordx2 v[10:11], v[6:7], off offset:144
	ds_read_b128 v[240:243], v2 offset:448
	ds_read_b128 v[244:247], v2 offset:480
	s_waitcnt lgkmcnt(4)
	s_waitcnt vmcnt(31)
	v_mul_f32_e32 v4, v104, v0
	v_mul_f32_e32 v3, v105, v0
	v_mul_f32_e32 v4, v208, v4
	v_mul_f32_e32 v3, v209, v3
	v_lshlrev_b32_e32 v14, 16, v164
	v_and_b32_e32 v164, 0xffff0000, v164
	v_mul_f32_e32 v4, v4, v14
	v_mul_f32_e32 v3, v3, v164
	v_cvt_pk_bf16_f32 v4, v4, v3
	v_mul_f32_e32 v5, v106, v0
	v_mul_f32_e32 v3, v107, v0
	v_mul_f32_e32 v5, v210, v5
	v_mul_f32_e32 v3, v211, v3
	v_lshlrev_b32_e32 v14, 16, v165
	v_and_b32_e32 v165, 0xffff0000, v165
	v_mul_f32_e32 v5, v5, v14
	v_mul_f32_e32 v3, v3, v165
	v_cvt_pk_bf16_f32 v5, v5, v3
	global_store_dwordx2 v[10:11], v[4:5], off offset:160
	s_waitcnt vmcnt(31)
	v_mul_f32_e32 v6, v108, v0
	v_mul_f32_e32 v9, v109, v0
	v_mul_f32_e32 v6, v212, v6
	v_mul_f32_e32 v9, v213, v9
	v_lshlrev_b32_e32 v15, 16, v166
	v_and_b32_e32 v166, 0xffff0000, v166
	v_mul_f32_e32 v6, v6, v15
	v_mul_f32_e32 v9, v9, v166
	v_cvt_pk_bf16_f32 v6, v6, v9
	v_mul_f32_e32 v7, v110, v0
	v_mul_f32_e32 v9, v111, v0
	v_mul_f32_e32 v7, v214, v7
	v_mul_f32_e32 v9, v215, v9
	v_lshlrev_b32_e32 v15, 16, v167
	v_and_b32_e32 v167, 0xffff0000, v167
	v_mul_f32_e32 v7, v7, v15
	v_mul_f32_e32 v9, v9, v167
	v_cvt_pk_bf16_f32 v7, v7, v9
	global_store_dwordx2 v[10:11], v[6:7], off offset:176
	ds_read_b128 v[208:211], v2 offset:512
	ds_read_b128 v[212:215], v2 offset:544
	s_waitcnt lgkmcnt(4)
	s_waitcnt vmcnt(31)
	v_mul_f32_e32 v4, v80, v0
	v_mul_f32_e32 v3, v81, v0
	v_mul_f32_e32 v4, v232, v4
	v_mul_f32_e32 v3, v233, v3
	v_lshlrev_b32_e32 v14, 16, v168
	v_and_b32_e32 v168, 0xffff0000, v168
	v_mul_f32_e32 v4, v4, v14
	v_mul_f32_e32 v3, v3, v168
	v_cvt_pk_bf16_f32 v4, v4, v3
	v_mul_f32_e32 v5, v82, v0
	v_mul_f32_e32 v3, v83, v0
	v_mul_f32_e32 v5, v234, v5
	v_mul_f32_e32 v3, v235, v3
	v_lshlrev_b32_e32 v14, 16, v169
	v_and_b32_e32 v169, 0xffff0000, v169
	v_mul_f32_e32 v5, v5, v14
	v_mul_f32_e32 v3, v3, v169
	v_cvt_pk_bf16_f32 v5, v5, v3
	global_store_dwordx2 v[10:11], v[4:5], off offset:192
	s_waitcnt vmcnt(31)
	v_mul_f32_e32 v6, v84, v0
	v_mul_f32_e32 v9, v85, v0
	v_mul_f32_e32 v6, v236, v6
	v_mul_f32_e32 v9, v237, v9
	v_lshlrev_b32_e32 v15, 16, v170
	v_and_b32_e32 v170, 0xffff0000, v170
	v_mul_f32_e32 v6, v6, v15
	v_mul_f32_e32 v9, v9, v170
	v_cvt_pk_bf16_f32 v6, v6, v9
	v_mul_f32_e32 v7, v86, v0
	v_mul_f32_e32 v9, v87, v0
	v_mul_f32_e32 v7, v238, v7
	v_mul_f32_e32 v9, v239, v9
	v_lshlrev_b32_e32 v15, 16, v171
	v_and_b32_e32 v171, 0xffff0000, v171
	v_mul_f32_e32 v7, v7, v15
	v_mul_f32_e32 v9, v9, v171
	v_cvt_pk_bf16_f32 v7, v7, v9
	global_store_dwordx2 v[10:11], v[6:7], off offset:208
	ds_read_b128 v[232:235], v2 offset:576
	ds_read_b128 v[236:239], v2 offset:608
	s_waitcnt lgkmcnt(4)
	s_waitcnt vmcnt(31)
	v_mul_f32_e32 v4, v88, v0
	v_mul_f32_e32 v3, v89, v0
	v_mul_f32_e32 v4, v240, v4
	v_mul_f32_e32 v3, v241, v3
	v_lshlrev_b32_e32 v14, 16, v172
	v_and_b32_e32 v172, 0xffff0000, v172
	v_mul_f32_e32 v4, v4, v14
	v_mul_f32_e32 v3, v3, v172
	v_cvt_pk_bf16_f32 v4, v4, v3
	v_mul_f32_e32 v5, v90, v0
	v_mul_f32_e32 v3, v91, v0
	v_mul_f32_e32 v5, v242, v5
	v_mul_f32_e32 v3, v243, v3
	v_lshlrev_b32_e32 v14, 16, v173
	v_and_b32_e32 v173, 0xffff0000, v173
	v_mul_f32_e32 v5, v5, v14
	v_mul_f32_e32 v3, v3, v173
	v_cvt_pk_bf16_f32 v5, v5, v3
	global_store_dwordx2 v[10:11], v[4:5], off offset:224
	s_waitcnt vmcnt(31)
	v_mul_f32_e32 v6, v92, v0
	v_mul_f32_e32 v9, v93, v0
	v_mul_f32_e32 v6, v244, v6
	v_mul_f32_e32 v9, v245, v9
	v_lshlrev_b32_e32 v15, 16, v174
	v_and_b32_e32 v174, 0xffff0000, v174
	v_mul_f32_e32 v6, v6, v15
	v_mul_f32_e32 v9, v9, v174
	v_cvt_pk_bf16_f32 v6, v6, v9
	v_mul_f32_e32 v7, v94, v0
	v_mul_f32_e32 v9, v95, v0
	v_mul_f32_e32 v7, v246, v7
	v_mul_f32_e32 v9, v247, v9
	v_lshlrev_b32_e32 v15, 16, v175
	v_and_b32_e32 v175, 0xffff0000, v175
	v_mul_f32_e32 v7, v7, v15
	v_mul_f32_e32 v9, v9, v175
	v_cvt_pk_bf16_f32 v7, v7, v9
	global_store_dwordx2 v[10:11], v[6:7], off offset:240
	ds_read_b128 v[240:243], v2 offset:640
	ds_read_b128 v[244:247], v2 offset:672
	s_waitcnt lgkmcnt(4)
	s_waitcnt vmcnt(31)
	v_mul_f32_e32 v4, v64, v0
	v_mul_f32_e32 v3, v65, v0
	v_mul_f32_e32 v4, v208, v4
	v_mul_f32_e32 v3, v209, v3
	v_lshlrev_b32_e32 v14, 16, v176
	v_and_b32_e32 v176, 0xffff0000, v176
	v_mul_f32_e32 v4, v4, v14
	v_mul_f32_e32 v3, v3, v176
	v_cvt_pk_bf16_f32 v4, v4, v3
	v_mul_f32_e32 v5, v66, v0
	v_mul_f32_e32 v3, v67, v0
	v_mul_f32_e32 v5, v210, v5
	v_mul_f32_e32 v3, v211, v3
	v_lshlrev_b32_e32 v14, 16, v177
	v_and_b32_e32 v177, 0xffff0000, v177
	v_mul_f32_e32 v5, v5, v14
	v_mul_f32_e32 v3, v3, v177
	v_cvt_pk_bf16_f32 v5, v5, v3
	global_store_dwordx2 v[10:11], v[4:5], off offset:256
	s_waitcnt vmcnt(31)
	v_mul_f32_e32 v6, v68, v0
	v_mul_f32_e32 v9, v69, v0
	v_mul_f32_e32 v6, v212, v6
	v_mul_f32_e32 v9, v213, v9
	v_lshlrev_b32_e32 v15, 16, v178
	v_and_b32_e32 v178, 0xffff0000, v178
	v_mul_f32_e32 v6, v6, v15
	v_mul_f32_e32 v9, v9, v178
	v_cvt_pk_bf16_f32 v6, v6, v9
	v_mul_f32_e32 v7, v70, v0
	v_mul_f32_e32 v9, v71, v0
	v_mul_f32_e32 v7, v214, v7
	v_mul_f32_e32 v9, v215, v9
	v_lshlrev_b32_e32 v15, 16, v179
	v_and_b32_e32 v179, 0xffff0000, v179
	v_mul_f32_e32 v7, v7, v15
	v_mul_f32_e32 v9, v9, v179
	v_cvt_pk_bf16_f32 v7, v7, v9
	global_store_dwordx2 v[10:11], v[6:7], off offset:272
	ds_read_b128 v[208:211], v2 offset:704
	ds_read_b128 v[212:215], v2 offset:736
	s_waitcnt lgkmcnt(4)
	s_waitcnt vmcnt(31)
	v_mul_f32_e32 v4, v72, v0
	v_mul_f32_e32 v3, v73, v0
	v_mul_f32_e32 v4, v232, v4
	v_mul_f32_e32 v3, v233, v3
	v_lshlrev_b32_e32 v14, 16, v180
	v_and_b32_e32 v180, 0xffff0000, v180
	v_mul_f32_e32 v4, v4, v14
	v_mul_f32_e32 v3, v3, v180
	v_cvt_pk_bf16_f32 v4, v4, v3
	v_mul_f32_e32 v5, v74, v0
	v_mul_f32_e32 v3, v75, v0
	v_mul_f32_e32 v5, v234, v5
	v_mul_f32_e32 v3, v235, v3
	v_lshlrev_b32_e32 v14, 16, v181
	v_and_b32_e32 v181, 0xffff0000, v181
	v_mul_f32_e32 v5, v5, v14
	v_mul_f32_e32 v3, v3, v181
	v_cvt_pk_bf16_f32 v5, v5, v3
	global_store_dwordx2 v[10:11], v[4:5], off offset:288
	s_waitcnt vmcnt(31)
	v_mul_f32_e32 v6, v76, v0
	v_mul_f32_e32 v9, v77, v0
	v_mul_f32_e32 v6, v236, v6
	v_mul_f32_e32 v9, v237, v9
	v_lshlrev_b32_e32 v15, 16, v182
	v_and_b32_e32 v182, 0xffff0000, v182
	v_mul_f32_e32 v6, v6, v15
	v_mul_f32_e32 v9, v9, v182
	v_cvt_pk_bf16_f32 v6, v6, v9
	v_mul_f32_e32 v7, v78, v0
	v_mul_f32_e32 v9, v79, v0
	v_mul_f32_e32 v7, v238, v7
	v_mul_f32_e32 v9, v239, v9
	v_lshlrev_b32_e32 v15, 16, v183
	v_and_b32_e32 v183, 0xffff0000, v183
	v_mul_f32_e32 v7, v7, v15
	v_mul_f32_e32 v9, v9, v183
	v_cvt_pk_bf16_f32 v7, v7, v9
	global_store_dwordx2 v[10:11], v[6:7], off offset:304
	ds_read_b128 v[232:235], v2 offset:768
	ds_read_b128 v[236:239], v2 offset:800
	s_waitcnt lgkmcnt(4)
	s_waitcnt vmcnt(31)
	v_mul_f32_e32 v4, v48, v0
	v_mul_f32_e32 v3, v49, v0
	v_mul_f32_e32 v4, v240, v4
	v_mul_f32_e32 v3, v241, v3
	v_lshlrev_b32_e32 v14, 16, v184
	v_and_b32_e32 v184, 0xffff0000, v184
	v_mul_f32_e32 v4, v4, v14
	v_mul_f32_e32 v3, v3, v184
	v_cvt_pk_bf16_f32 v4, v4, v3
	v_mul_f32_e32 v5, v50, v0
	v_mul_f32_e32 v3, v51, v0
	v_mul_f32_e32 v5, v242, v5
	v_mul_f32_e32 v3, v243, v3
	v_lshlrev_b32_e32 v14, 16, v185
	v_and_b32_e32 v185, 0xffff0000, v185
	v_mul_f32_e32 v5, v5, v14
	v_mul_f32_e32 v3, v3, v185
	v_cvt_pk_bf16_f32 v5, v5, v3
	global_store_dwordx2 v[10:11], v[4:5], off offset:320
	s_waitcnt vmcnt(31)
	v_mul_f32_e32 v6, v52, v0
	v_mul_f32_e32 v9, v53, v0
	v_mul_f32_e32 v6, v244, v6
	v_mul_f32_e32 v9, v245, v9
	v_lshlrev_b32_e32 v15, 16, v186
	v_and_b32_e32 v186, 0xffff0000, v186
	v_mul_f32_e32 v6, v6, v15
	v_mul_f32_e32 v9, v9, v186
	v_cvt_pk_bf16_f32 v6, v6, v9
	v_mul_f32_e32 v7, v54, v0
	v_mul_f32_e32 v9, v55, v0
	v_mul_f32_e32 v7, v246, v7
	v_mul_f32_e32 v9, v247, v9
	v_lshlrev_b32_e32 v15, 16, v187
	v_and_b32_e32 v187, 0xffff0000, v187
	v_mul_f32_e32 v7, v7, v15
	v_mul_f32_e32 v9, v9, v187
	v_cvt_pk_bf16_f32 v7, v7, v9
	global_store_dwordx2 v[10:11], v[6:7], off offset:336
	ds_read_b128 v[240:243], v2 offset:832
	ds_read_b128 v[244:247], v2 offset:864
	s_waitcnt lgkmcnt(4)
	s_waitcnt vmcnt(31)
	v_mul_f32_e32 v4, v56, v0
	v_mul_f32_e32 v3, v57, v0
	v_mul_f32_e32 v4, v208, v4
	v_mul_f32_e32 v3, v209, v3
	v_lshlrev_b32_e32 v14, 16, v188
	v_and_b32_e32 v188, 0xffff0000, v188
	v_mul_f32_e32 v4, v4, v14
	v_mul_f32_e32 v3, v3, v188
	v_cvt_pk_bf16_f32 v4, v4, v3
	v_mul_f32_e32 v5, v58, v0
	v_mul_f32_e32 v3, v59, v0
	v_mul_f32_e32 v5, v210, v5
	v_mul_f32_e32 v3, v211, v3
	v_lshlrev_b32_e32 v14, 16, v189
	v_and_b32_e32 v189, 0xffff0000, v189
	v_mul_f32_e32 v5, v5, v14
	v_mul_f32_e32 v3, v3, v189
	v_cvt_pk_bf16_f32 v5, v5, v3
	global_store_dwordx2 v[10:11], v[4:5], off offset:352
	s_waitcnt vmcnt(31)
	v_mul_f32_e32 v6, v60, v0
	v_mul_f32_e32 v9, v61, v0
	v_mul_f32_e32 v6, v212, v6
	v_mul_f32_e32 v9, v213, v9
	v_lshlrev_b32_e32 v15, 16, v190
	v_and_b32_e32 v190, 0xffff0000, v190
	v_mul_f32_e32 v6, v6, v15
	v_mul_f32_e32 v9, v9, v190
	v_cvt_pk_bf16_f32 v6, v6, v9
	v_mul_f32_e32 v7, v62, v0
	v_mul_f32_e32 v9, v63, v0
	v_mul_f32_e32 v7, v214, v7
	v_mul_f32_e32 v9, v215, v9
	v_lshlrev_b32_e32 v15, 16, v191
	v_and_b32_e32 v191, 0xffff0000, v191
	v_mul_f32_e32 v7, v7, v15
	v_mul_f32_e32 v9, v9, v191
	v_cvt_pk_bf16_f32 v7, v7, v9
	global_store_dwordx2 v[10:11], v[6:7], off offset:368
	ds_read_b128 v[208:211], v2 offset:896
	ds_read_b128 v[212:215], v2 offset:928
	s_waitcnt lgkmcnt(4)
	s_waitcnt vmcnt(31)
	v_mul_f32_e32 v4, v32, v0
	v_mul_f32_e32 v3, v33, v0
	v_mul_f32_e32 v4, v232, v4
	v_mul_f32_e32 v3, v233, v3
	v_lshlrev_b32_e32 v14, 16, v216
	v_and_b32_e32 v216, 0xffff0000, v216
	v_mul_f32_e32 v4, v4, v14
	v_mul_f32_e32 v3, v3, v216
	v_cvt_pk_bf16_f32 v4, v4, v3
	v_mul_f32_e32 v5, v34, v0
	v_mul_f32_e32 v3, v35, v0
	v_mul_f32_e32 v5, v234, v5
	v_mul_f32_e32 v3, v235, v3
	v_lshlrev_b32_e32 v14, 16, v217
	v_and_b32_e32 v217, 0xffff0000, v217
	v_mul_f32_e32 v5, v5, v14
	v_mul_f32_e32 v3, v3, v217
	v_cvt_pk_bf16_f32 v5, v5, v3
	global_store_dwordx2 v[10:11], v[4:5], off offset:384
	s_waitcnt vmcnt(31)
	v_mul_f32_e32 v6, v36, v0
	v_mul_f32_e32 v9, v37, v0
	v_mul_f32_e32 v6, v236, v6
	v_mul_f32_e32 v9, v237, v9
	v_lshlrev_b32_e32 v15, 16, v218
	v_and_b32_e32 v218, 0xffff0000, v218
	v_mul_f32_e32 v6, v6, v15
	v_mul_f32_e32 v9, v9, v218
	v_cvt_pk_bf16_f32 v6, v6, v9
	v_mul_f32_e32 v7, v38, v0
	v_mul_f32_e32 v9, v39, v0
	v_mul_f32_e32 v7, v238, v7
	v_mul_f32_e32 v9, v239, v9
	v_lshlrev_b32_e32 v15, 16, v219
	v_and_b32_e32 v219, 0xffff0000, v219
	v_mul_f32_e32 v7, v7, v15
	v_mul_f32_e32 v9, v9, v219
	v_cvt_pk_bf16_f32 v7, v7, v9
	global_store_dwordx2 v[10:11], v[6:7], off offset:400
	ds_read_b128 v[232:235], v2 offset:960
	ds_read_b128 v[236:239], v2 offset:992
	s_waitcnt lgkmcnt(4)
	s_waitcnt vmcnt(31)
	v_mul_f32_e32 v4, v40, v0
	v_mul_f32_e32 v3, v41, v0
	v_mul_f32_e32 v4, v240, v4
	v_mul_f32_e32 v3, v241, v3
	v_lshlrev_b32_e32 v14, 16, v220
	v_and_b32_e32 v220, 0xffff0000, v220
	v_mul_f32_e32 v4, v4, v14
	v_mul_f32_e32 v3, v3, v220
	v_cvt_pk_bf16_f32 v4, v4, v3
	v_mul_f32_e32 v5, v42, v0
	v_mul_f32_e32 v3, v43, v0
	v_mul_f32_e32 v5, v242, v5
	v_mul_f32_e32 v3, v243, v3
	v_lshlrev_b32_e32 v14, 16, v221
	v_and_b32_e32 v221, 0xffff0000, v221
	v_mul_f32_e32 v5, v5, v14
	v_mul_f32_e32 v3, v3, v221
	v_cvt_pk_bf16_f32 v5, v5, v3
	global_store_dwordx2 v[10:11], v[4:5], off offset:416
	s_waitcnt vmcnt(31)
	v_mul_f32_e32 v6, v44, v0
	v_mul_f32_e32 v9, v45, v0
	v_mul_f32_e32 v6, v244, v6
	v_mul_f32_e32 v9, v245, v9
	v_lshlrev_b32_e32 v15, 16, v222
	v_and_b32_e32 v222, 0xffff0000, v222
	v_mul_f32_e32 v6, v6, v15
	v_mul_f32_e32 v9, v9, v222
	v_cvt_pk_bf16_f32 v6, v6, v9
	v_mul_f32_e32 v7, v46, v0
	v_mul_f32_e32 v9, v47, v0
	v_mul_f32_e32 v7, v246, v7
	v_mul_f32_e32 v9, v247, v9
	v_lshlrev_b32_e32 v15, 16, v223
	v_and_b32_e32 v223, 0xffff0000, v223
	v_mul_f32_e32 v7, v7, v15
	v_mul_f32_e32 v9, v9, v223
	v_cvt_pk_bf16_f32 v7, v7, v9
	global_store_dwordx2 v[10:11], v[6:7], off offset:432
	s_waitcnt lgkmcnt(2)
	s_waitcnt vmcnt(31)
	v_mul_f32_e32 v4, v16, v0
	v_mul_f32_e32 v3, v17, v0
	v_mul_f32_e32 v4, v208, v4
	v_mul_f32_e32 v3, v209, v3
	v_lshlrev_b32_e32 v14, 16, v224
	v_and_b32_e32 v224, 0xffff0000, v224
	v_mul_f32_e32 v4, v4, v14
	v_mul_f32_e32 v3, v3, v224
	v_cvt_pk_bf16_f32 v4, v4, v3
	v_mul_f32_e32 v5, v18, v0
	v_mul_f32_e32 v3, v19, v0
	v_mul_f32_e32 v5, v210, v5
	v_mul_f32_e32 v3, v211, v3
	v_lshlrev_b32_e32 v14, 16, v225
	v_and_b32_e32 v225, 0xffff0000, v225
	v_mul_f32_e32 v5, v5, v14
	v_mul_f32_e32 v3, v3, v225
	v_cvt_pk_bf16_f32 v5, v5, v3
	global_store_dwordx2 v[10:11], v[4:5], off offset:448
	s_waitcnt vmcnt(31)
	v_mul_f32_e32 v6, v20, v0
	v_mul_f32_e32 v9, v21, v0
	v_mul_f32_e32 v6, v212, v6
	v_mul_f32_e32 v9, v213, v9
	v_lshlrev_b32_e32 v15, 16, v226
	v_and_b32_e32 v226, 0xffff0000, v226
	v_mul_f32_e32 v6, v6, v15
	v_mul_f32_e32 v9, v9, v226
	v_cvt_pk_bf16_f32 v6, v6, v9
	v_mul_f32_e32 v7, v22, v0
	v_mul_f32_e32 v9, v23, v0
	v_mul_f32_e32 v7, v214, v7
	v_mul_f32_e32 v9, v215, v9
	v_lshlrev_b32_e32 v15, 16, v227
	v_and_b32_e32 v227, 0xffff0000, v227
	v_mul_f32_e32 v7, v7, v15
	v_mul_f32_e32 v9, v9, v227
	v_cvt_pk_bf16_f32 v7, v7, v9
	global_store_dwordx2 v[10:11], v[6:7], off offset:464
	s_waitcnt lgkmcnt(0)
	s_waitcnt vmcnt(31)
	v_mul_f32_e32 v4, v24, v0
	v_mul_f32_e32 v3, v25, v0
	v_mul_f32_e32 v4, v232, v4
	v_mul_f32_e32 v3, v233, v3
	v_lshlrev_b32_e32 v14, 16, v228
	v_and_b32_e32 v228, 0xffff0000, v228
	v_mul_f32_e32 v4, v4, v14
	v_mul_f32_e32 v3, v3, v228
	v_cvt_pk_bf16_f32 v4, v4, v3
	v_mul_f32_e32 v5, v26, v0
	v_mul_f32_e32 v3, v27, v0
	v_mul_f32_e32 v5, v234, v5
	v_mul_f32_e32 v3, v235, v3
	v_lshlrev_b32_e32 v14, 16, v229
	v_and_b32_e32 v229, 0xffff0000, v229
	v_mul_f32_e32 v5, v5, v14
	v_mul_f32_e32 v3, v3, v229
	v_cvt_pk_bf16_f32 v5, v5, v3
	global_store_dwordx2 v[10:11], v[4:5], off offset:480
	s_waitcnt vmcnt(31)
	v_mul_f32_e32 v6, v28, v0
	v_mul_f32_e32 v9, v29, v0
	v_mul_f32_e32 v6, v236, v6
	v_mul_f32_e32 v9, v237, v9
	v_lshlrev_b32_e32 v15, 16, v230
	v_and_b32_e32 v230, 0xffff0000, v230
	v_mul_f32_e32 v6, v6, v15
	v_mul_f32_e32 v9, v9, v230
	v_cvt_pk_bf16_f32 v6, v6, v9
	v_mul_f32_e32 v7, v30, v0
	v_mul_f32_e32 v9, v31, v0
	v_mul_f32_e32 v7, v238, v7
	v_mul_f32_e32 v9, v239, v9
	v_lshlrev_b32_e32 v15, 16, v231
	v_and_b32_e32 v231, 0xffff0000, v231
	v_mul_f32_e32 v7, v7, v15
	v_mul_f32_e32 v9, v9, v231
	v_cvt_pk_bf16_f32 v7, v7, v9
	global_store_dwordx2 v[10:11], v[6:7], off offset:496
	s_branch .LBB0_306
